# B mixer ctx sub-blocks: all 16 LDS reads (K and V fragments) issued at block top into own registers, counted lgkmcnt waits
# speedup vs baseline: 1.0035x; 1.0035x over previous
; template <int MODE, int NKB> ...
;     ...
;     f32x4 st[NS][NKB];
; #pragma unroll
;     for (int i = 0; i < NKB; ++i) { const LAS bf16_t* kp = Ks + (kb0 + 16 * i + l15) * KST + 8 * quad;
; #pragma unroll
;         for (int s = 0; s < NS; ++s) st[s][i] = (f32x4){negm, negm, negm, negm};
; #pragma unroll
;         for (int kc = 0; kc < 2; ++kc) {
;             if (MODE == 2) {
; #pragma unroll
;                 for (int s = 0; s < NS; ++s) { const bf16x8 a = *(const LAS bf16x8*)(kp + 64 * s + 32 * kc); st[s][i] = __builtin_amdgcn_mfma_f32_16x16x32_bf16(a, qf[s][kc], st[s][i], 0, 0, 0); }
;                 if (kc == 1 && (i & 1)) __builtin_amdgcn_sched_barrier(0);
;             } else { const bf16x8 a = *(const LAS bf16x8*)(kp + 32 * kc);
; #pragma unroll
;                 for (int s = 0; s < NS; ++s) st[s][i] = __builtin_amdgcn_mfma_f32_16x16x32_bf16(a, qf[s][kc], st[s][i], 0, 0, 0); } } }
;     if (MODE == 2) __builtin_amdgcn_sched_barrier(0);
;     if (masked) {
;         if (MODE == 0) {
; #pragma unroll
;             for (int i = 0; i < NKB; ++i)
; #pragma unroll
;                 for (int r = 0; r < 4; ++r) { const int d = mp - (kb0 + 16 * i + 4 * quad + r); const bool bad = (d > 128) || (d < -128);
; #pragma unroll
;                     for (int s = 0; s < NS; ++s) st[s][i][r] = bad ? NEGBIG : st[s][i][r]; }
;         }
;         if (MODE == 1) {
; #pragma unroll
;             for (int i = 0; i < NKB; ++i)
; #pragma unroll
;                 for (int r = 0; r < 4; ++r) { const int key = kb0 + 16 * i + 4 * quad + r; const bool valid = (key >= mp) && (key < mp + 16);
;                     const float bias = valid ? brow[key] : 0.f; st[0][i][r] = valid ? st[0][i][r] + bias : NEGBIG; }
;         }
;     }
;     bf16x8 pf[NS][NKB / 2];
; #pragma unroll
;     for (int s = 0; s < NS; ++s) {
;         if (MODE == 2) __builtin_amdgcn_sched_barrier(0);
;         float ps = 0.f;
; #pragma unroll
;         for (int i = 0; i < NKB; ++i)
; #pragma unroll
;             for (int r = 0; r < 4; ++r) { const float p = fast_exp2(st[s][i][r]); st[s][i][r] = p; ps += p; }
;         lsum[s] += ps;
; #pragma unroll
;         for (int c = 0; c < NKB / 2; ++c) { u32x4 pw; pw.x = pk2(st[s][2 * c][0], st[s][2 * c][1]); pw.y = pk2(st[s][2 * c][2], st[s][2 * c][3]); pw.z = pk2(st[s][2 * c + 1][0], st[s][2 * c + 1][1]); pw.w = pk2(st[s][2 * c + 1][2], st[s][2 * c + 1][3]);
.LBB0_484:
	v_add_u32_e32 v154, 0x4800, v124
	v_add_u32_e32 v155, 0x5800, v124
	v_add_u32_e32 v156, 0x6800, v124
	v_add_u32_e32 v162, 0x7800, v124
	ds_read_b128 v[138:141], v126
	ds_read_b128 v[142:145], v126 offset:64
	ds_read_b128 v[146:149], v126 offset:2304
	ds_read_b128 v[150:153], v126 offset:2368
	ds_read_b128 v[158:161], v126 offset:4608
	ds_read_b128 v[170:173], v126 offset:4672
	ds_read_b128 v[182:185], v126 offset:6912
	ds_read_b128 v[186:189], v126 offset:6976
	ds_read2_b64 v[190:193], v154 offset1:4
	ds_read2_b64 v[202:205], v154 offset0:8 offset1:12
	ds_read2_b64 v[210:213], v155 offset0:32 offset1:36
	ds_read2_b64 v[214:217], v155 offset0:40 offset1:44
	ds_read2_b64 v[218:221], v156 offset0:64 offset1:68
	ds_read2_b64 v[222:225], v156 offset0:72 offset1:76
	ds_read2_b64 v[240:243], v162 offset0:96 offset1:100
	s_nop 0
	s_nop 0
	s_nop 0
	s_waitcnt lgkmcnt(14)
	v_mfma_f32_16x16x32_bf16 v[84:87], v[138:141], v[28:31], v[24:27]
	ds_read2_b64 v[244:247], v162 offset0:104 offset1:108
	s_nop 0
	s_nop 0
	s_nop 0
	s_nop 0
	s_waitcnt lgkmcnt(14)
	v_mfma_f32_16x16x32_bf16 v[84:87], v[142:145], v[32:35], v[84:87]
	s_nop 0
	s_nop 0
	s_waitcnt lgkmcnt(13)
	v_mfma_f32_16x16x32_bf16 v[88:91], v[146:149], v[28:31], v[24:27]
	s_nop 4
	v_exp_f32_e32 v84, v84
	v_exp_f32_e32 v85, v85
	v_exp_f32_e32 v86, v86
	s_waitcnt lgkmcnt(12)
	v_mfma_f32_16x16x32_bf16 v[88:91], v[150:153], v[32:35], v[88:91]
	s_nop 0
	v_exp_f32_e32 v87, v87
	v_add_f32_e32 v125, 0, v84
	s_nop 0
	s_waitcnt lgkmcnt(11)
	v_mfma_f32_16x16x32_bf16 v[92:95], v[158:161], v[28:31], v[24:27]
	s_nop 2
	v_exp_f32_e32 v88, v88
	v_exp_f32_e32 v89, v89
	v_add_f32_e32 v125, v85, v125
	s_waitcnt lgkmcnt(10)
	v_mfma_f32_16x16x32_bf16 v[92:95], v[170:173], v[32:35], v[92:95]
	s_nop 0
	v_add_f32_e32 v125, v86, v125
	v_add_f32_e32 v125, v87, v125
	v_add_f32_e32 v125, v125, v88
	v_exp_f32_e32 v90, v90
	v_exp_f32_e32 v91, v91
	s_nop 0
	s_waitcnt lgkmcnt(9)
	v_mfma_f32_16x16x32_bf16 v[96:99], v[182:185], v[28:31], v[24:27]
	v_exp_f32_e32 v92, v92
	v_add_f32_e32 v125, v89, v125
	v_exp_f32_e32 v93, v93
	s_waitcnt lgkmcnt(8)
	v_mfma_f32_16x16x32_bf16 v[96:99], v[186:189], v[32:35], v[96:99]
	v_cvt_pk_bf16_f32 v130, v88, v89
	s_nop 0
	v_cvt_pk_bf16_f32 v128, v84, v85
	v_cvt_pk_bf16_f32 v129, v86, v87
	s_nop 0
	v_add_f32_e32 v125, v90, v125
	v_exp_f32_e32 v94, v94
	v_add_f32_e32 v125, v91, v125
	v_exp_f32_e32 v95, v95
	v_add_f32_e32 v125, v125, v92
	v_exp_f32_e32 v127, v96
	v_add_f32_e32 v125, v93, v125
	v_cvt_pk_bf16_f32 v131, v90, v91
	v_add_f32_e32 v125, v94, v125
	v_add_f32_e32 v125, v95, v125
	s_nop 0
	s_waitcnt lgkmcnt(7)
	v_mfma_f32_16x16x32_bf16 v[68:71], v[190:193], v[128:131], v[68:71]
	s_nop 0
	v_add_f32_e32 v96, v125, v127
	v_exp_f32_e32 v125, v97
	v_exp_f32_e32 v134, v98
	v_exp_f32_e32 v99, v99
	v_cvt_pk_bf16_f32 v97, v94, v95
	v_add_f32_e32 v96, v125, v96
	v_add_f32_e32 v96, v134, v96
	v_add_f32_e32 v135, v99, v96
	v_cvt_pk_bf16_f32 v96, v92, v93
	v_cvt_pk_bf16_f32 v98, v127, v125
	v_cvt_pk_bf16_f32 v99, v134, v99
	s_nop 0
	v_add_f32_e32 v125, v119, v135
	s_nop 0
	s_waitcnt lgkmcnt(6)
	v_mfma_f32_16x16x32_bf16 v[84:87], v[202:205], v[96:99], v[68:71]
	s_nop 2
	s_nop 0
	s_nop 0
	s_waitcnt lgkmcnt(5)
	v_mfma_f32_16x16x32_bf16 v[68:71], v[210:213], v[128:131], v[72:75]
	s_nop 2
	s_nop 0
	s_nop 0
	s_waitcnt lgkmcnt(4)
	v_mfma_f32_16x16x32_bf16 v[88:91], v[214:217], v[96:99], v[68:71]
	s_nop 0
	s_nop 1
	s_nop 0
	s_nop 0
	s_nop 0
	s_waitcnt lgkmcnt(3)
	v_mfma_f32_16x16x32_bf16 v[68:71], v[218:221], v[128:131], v[76:79]
	s_nop 0
	s_waitcnt lgkmcnt(2)
	v_mfma_f32_16x16x32_bf16 v[92:95], v[222:225], v[96:99], v[68:71]
	s_nop 0
	s_nop 4
	s_nop 0
	s_nop 0
	s_nop 0
	s_waitcnt lgkmcnt(1)
	v_mfma_f32_16x16x32_bf16 v[68:71], v[240:243], v[128:131], v[80:83]
	s_nop 0
	s_waitcnt lgkmcnt(0)
	v_mfma_f32_16x16x32_bf16 v[96:99], v[244:247], v[96:99], v[68:71]

; template <int MODE, int NKB> ...
;     ...
;     f32x4 st[NS][NKB];
; #pragma unroll
;     for (int i = 0; i < NKB; ++i) { const LAS bf16_t* kp = Ks + (kb0 + 16 * i + l15) * KST + 8 * quad;
; #pragma unroll
;         for (int s = 0; s < NS; ++s) st[s][i] = (f32x4){negm, negm, negm, negm};
; #pragma unroll
;         for (int kc = 0; kc < 2; ++kc) {
;             if (MODE == 2) {
; #pragma unroll
;                 for (int s = 0; s < NS; ++s) { const bf16x8 a = *(const LAS bf16x8*)(kp + 64 * s + 32 * kc); st[s][i] = __builtin_amdgcn_mfma_f32_16x16x32_bf16(a, qf[s][kc], st[s][i], 0, 0, 0); }
;                 if (kc == 1 && (i & 1)) __builtin_amdgcn_sched_barrier(0);
;             } else { const bf16x8 a = *(const LAS bf16x8*)(kp + 32 * kc);
; #pragma unroll
;                 for (int s = 0; s < NS; ++s) st[s][i] = __builtin_amdgcn_mfma_f32_16x16x32_bf16(a, qf[s][kc], st[s][i], 0, 0, 0); } } }
;     if (MODE == 2) __builtin_amdgcn_sched_barrier(0);
;     if (masked) {
;         if (MODE == 0) {
; #pragma unroll
;             for (int i = 0; i < NKB; ++i)
; #pragma unroll
;                 for (int r = 0; r < 4; ++r) { const int d = mp - (kb0 + 16 * i + 4 * quad + r); const bool bad = (d > 128) || (d < -128);
; #pragma unroll
;                     for (int s = 0; s < NS; ++s) st[s][i][r] = bad ? NEGBIG : st[s][i][r]; }
;         }
;         if (MODE == 1) {
; #pragma unroll
;             for (int i = 0; i < NKB; ++i)
; #pragma unroll
;                 for (int r = 0; r < 4; ++r) { const int key = kb0 + 16 * i + 4 * quad + r; const bool valid = (key >= mp) && (key < mp + 16);
;                     const float bias = valid ? brow[key] : 0.f; st[0][i][r] = valid ? st[0][i][r] + bias : NEGBIG; }
;         }
;     }
;     bf16x8 pf[NS][NKB / 2];
; #pragma unroll
;     for (int s = 0; s < NS; ++s) {
;         if (MODE == 2) __builtin_amdgcn_sched_barrier(0);
;         float ps = 0.f;
; #pragma unroll
;         for (int i = 0; i < NKB; ++i)
; #pragma unroll
;             for (int r = 0; r < 4; ++r) { const float p = fast_exp2(st[s][i][r]); st[s][i][r] = p; ps += p; }
;         lsum[s] += ps;
; #pragma unroll
;         for (int c = 0; c < NKB / 2; ++c) { u32x4 pw; pw.x = pk2(st[s][2 * c][0], st[s][2 * c][1]); pw.y = pk2(st[s][2 * c][2], st[s][2 * c][3]); pw.z = pk2(st[s][2 * c + 1][0], st[s][2 * c + 1][1]); pw.w = pk2(st[s][2 * c + 1][2], st[s][2 * c + 1][3]);
.LBB0_506:
	v_add_u32_e32 v154, 0x4800, v124
	v_add_u32_e32 v155, 0x5800, v124
	v_add_u32_e32 v156, 0x6800, v124
	v_add_u32_e32 v162, 0x7800, v124
	ds_read_b128 v[138:141], v126 offset:9216
	ds_read_b128 v[142:145], v126 offset:9280
	ds_read_b128 v[146:149], v126 offset:11520
	ds_read_b128 v[150:153], v126 offset:11584
	ds_read_b128 v[158:161], v126 offset:13824
	ds_read_b128 v[170:173], v126 offset:13888
	ds_read_b128 v[182:185], v126 offset:16128
	ds_read_b128 v[186:189], v126 offset:16192
	ds_read2_b64 v[190:193], v154 offset0:16 offset1:20
	ds_read2_b64 v[202:205], v154 offset0:24 offset1:28
	ds_read2_b64 v[210:213], v155 offset0:48 offset1:52
	ds_read2_b64 v[214:217], v155 offset0:56 offset1:60
	ds_read2_b64 v[218:221], v156 offset0:80 offset1:84
	ds_read2_b64 v[222:225], v156 offset0:88 offset1:92
	ds_read2_b64 v[240:243], v162 offset0:112 offset1:116
	s_nop 0
	s_nop 0
	s_nop 0
	s_nop 0
	s_waitcnt lgkmcnt(14)
	v_mfma_f32_16x16x32_bf16 v[68:71], v[138:141], v[28:31], v[24:27]
	ds_read2_b64 v[244:247], v162 offset0:120 offset1:124
	s_nop 0
	s_nop 0
	s_nop 0
	s_waitcnt lgkmcnt(14)
	v_mfma_f32_16x16x32_bf16 v[68:71], v[142:145], v[32:35], v[68:71]
	s_nop 0
	s_nop 0
	s_waitcnt lgkmcnt(13)
	v_mfma_f32_16x16x32_bf16 v[72:75], v[146:149], v[28:31], v[24:27]
	s_nop 4
	v_exp_f32_e32 v68, v68
	v_exp_f32_e32 v69, v69
	v_exp_f32_e32 v70, v70
	s_waitcnt lgkmcnt(12)
	v_mfma_f32_16x16x32_bf16 v[72:75], v[150:153], v[32:35], v[72:75]
	s_nop 0
	v_exp_f32_e32 v71, v71
	v_add_f32_e32 v119, 0, v68
	v_add_f32_e32 v119, v69, v119
	v_add_f32_e32 v119, v70, v119
	s_nop 2
	v_exp_f32_e32 v72, v72
	v_exp_f32_e32 v73, v73
	s_nop 0
	s_waitcnt lgkmcnt(11)
	v_mfma_f32_16x16x32_bf16 v[76:79], v[158:161], v[28:31], v[24:27]
	v_exp_f32_e32 v74, v74
	v_add_f32_e32 v119, v71, v119
	v_exp_f32_e32 v75, v75
	s_waitcnt lgkmcnt(10)
	v_mfma_f32_16x16x32_bf16 v[76:79], v[170:173], v[32:35], v[76:79]
	s_nop 0
	s_nop 0
	v_add_f32_e32 v119, v119, v72
	v_add_f32_e32 v119, v73, v119
	v_add_f32_e32 v119, v74, v119
	s_nop 2
	v_exp_f32_e32 v76, v76
	s_nop 0
	s_waitcnt lgkmcnt(9)
	v_mfma_f32_16x16x32_bf16 v[80:83], v[182:185], v[28:31], v[24:27]
	v_exp_f32_e32 v77, v77
	v_exp_f32_e32 v78, v78
	v_add_f32_e32 v119, v75, v119
	s_nop 0
	s_waitcnt lgkmcnt(8)
	v_mfma_f32_16x16x32_bf16 v[80:83], v[186:189], v[32:35], v[80:83]
	v_cvt_pk_bf16_f32 v128, v72, v73
	s_nop 0
	v_cvt_pk_bf16_f32 v126, v68, v69
	v_cvt_pk_bf16_f32 v127, v70, v71
	s_nop 0
	v_exp_f32_e32 v79, v79
	v_add_f32_e32 v119, v119, v76
	s_nop 0
	v_exp_f32_e32 v130, v80
	v_add_f32_e32 v119, v77, v119
	v_add_f32_e32 v119, v78, v119
	v_cvt_pk_bf16_f32 v129, v74, v75
	s_nop 0
	v_add_f32_e32 v119, v79, v119
	v_add_f32_e32 v80, v119, v130
	v_exp_f32_e32 v119, v81
	v_exp_f32_e32 v131, v82
	v_exp_f32_e32 v83, v83
	s_nop 0
	s_waitcnt lgkmcnt(7)
	v_mfma_f32_16x16x32_bf16 v[68:71], v[190:193], v[126:129], v[84:87]
	v_add_f32_e32 v80, v119, v80
	v_add_f32_e32 v80, v131, v80
	v_add_f32_e32 v134, v83, v80
	v_cvt_pk_bf16_f32 v80, v76, v77
	v_cvt_pk_bf16_f32 v81, v78, v79
	v_cvt_pk_bf16_f32 v82, v130, v119
	v_cvt_pk_bf16_f32 v83, v131, v83
	s_nop 0
	s_nop 0
	s_nop 0
	s_waitcnt lgkmcnt(6)
	v_mfma_f32_16x16x32_bf16 v[68:71], v[202:205], v[80:83], v[68:71]
	s_nop 0
	s_nop 0
	v_add_f32_e32 v119, v125, v134
	s_nop 0
	s_waitcnt lgkmcnt(5)
	v_mfma_f32_16x16x32_bf16 v[72:75], v[210:213], v[126:129], v[88:91]
	s_nop 2
	s_nop 0
	s_nop 0
	s_waitcnt lgkmcnt(4)
	v_mfma_f32_16x16x32_bf16 v[72:75], v[214:217], v[80:83], v[72:75]
	s_nop 0
	s_nop 0
	s_nop 0
	s_waitcnt lgkmcnt(3)
	v_mfma_f32_16x16x32_bf16 v[76:79], v[218:221], v[126:129], v[92:95]
	s_nop 0
	s_waitcnt lgkmcnt(2)
	v_mfma_f32_16x16x32_bf16 v[76:79], v[222:225], v[80:83], v[76:79]
	s_nop 0
	s_nop 0
	s_nop 0
	s_waitcnt lgkmcnt(1)
	v_mfma_f32_16x16x32_bf16 v[84:87], v[240:243], v[126:129], v[96:99]
	s_nop 0
	s_waitcnt lgkmcnt(0)
	v_mfma_f32_16x16x32_bf16 v[80:83], v[244:247], v[80:83], v[84:87]
	s_branch .LBB0_453
